# P12 residual epilogue re-emitted batched (16 residual loads in flight instead of 32 dependent load/store round trips)
# baseline (speedup 1.0000x reference)
.LBB0_1338:
	s_mul_hi_i32 s11, s18, 0x38e38e39
	s_lshr_b32 s13, s11, 31
	s_ashr_i32 s11, s11, 1
	s_add_i32 s11, s11, s13
	s_mul_i32 s13, s11, 9
	s_sub_i32 s13, s18, s13
	s_mul_i32 s11, s11, 6
	s_cmp_lg_u32 s13, 0
	s_cselect_b32 s20, s11, 24
	s_ashr_i32 s21, s20, 31
	s_lshl_b64 s[20:21], s[20:21], 13
	s_add_u32 s11, s40, s20
	s_addc_u32 s13, s41, s21
	s_lshl_b32 s20, s19, 8
	s_ashr_i32 s21, s20, 31
	s_lshl_b64 s[20:21], s[20:21], 2
	s_add_u32 s11, s11, s20
	s_addc_u32 s13, s13, s21
	s_add_u32 s22, s11, s50
	s_addc_u32 s23, s13, 0
	s_lshl_b32 s18, s18, 8
	v_mov_b32_e32 v158, v161
	v_mov_b32_e32 v76, v162
	s_ashr_i32 s19, s18, 31
	s_add_u32 s11, s46, s20
	v_lshlrev_b32_e32 v76, 2, v76
	s_addc_u32 s13, s47, s21
	s_lshl_b64 s[18:19], s[18:19], 13
	v_ashrrev_i32_e32 v77, 31, v76
	s_add_u32 s18, s11, s18
	v_add_u32_e32 v158, s42, v158
	v_lshlrev_b64 v[156:157], 2, v[76:77]
	s_addc_u32 s19, s13, s19
	v_ashrrev_i32_e32 v159, 31, v158
	v_lshl_add_u64 v[76:77], s[22:23], 0, v[156:157]
	v_lshl_add_u64 v[156:157], s[18:19], 0, v[156:157]
	v_lshlrev_b64 v[168:169], 13, v[158:159]
	v_lshl_add_u64 v[172:173], v[156:157], 0, v[168:169]
	s_mov_b64 s[18:19], -1
	s_andn2_b64 vcc, exec, s[0:1]
	global_load_dwordx4 v[132:135], v[76:77], off
	global_load_dwordx4 v[128:131], v[76:77], off offset:64
	global_load_dwordx4 v[120:123], v[76:77], off offset:512
	s_nop 0
	global_load_dwordx4 v[76:79], v[76:77], off offset:576
	v_ashrrev_i32_e32 v175, 31, v158
	v_lshlrev_b64 v[174:175], 13, v[158:159]
	v_lshl_add_u64 v[174:175], v[156:157], 0, v[174:175]
	global_load_dwordx4 v[176:179], v[174:175], off
	global_load_dwordx4 v[180:183], v[174:175], off offset:64
	global_load_dwordx4 v[184:187], v[174:175], off offset:512
	global_load_dwordx4 v[188:191], v[174:175], off offset:576
	v_add_u32_e32 v174, 16, v158
	v_ashrrev_i32_e32 v175, 31, v174
	v_lshlrev_b64 v[174:175], 13, v[174:175]
	v_lshl_add_u64 v[174:175], v[156:157], 0, v[174:175]
	global_load_dwordx4 v[192:195], v[174:175], off
	global_load_dwordx4 v[196:199], v[174:175], off offset:64
	global_load_dwordx4 v[200:203], v[174:175], off offset:512
	global_load_dwordx4 v[204:207], v[174:175], off offset:576
	v_add_u32_e32 v174, 32, v158
	v_ashrrev_i32_e32 v175, 31, v174
	v_lshlrev_b64 v[174:175], 13, v[174:175]
	v_lshl_add_u64 v[174:175], v[156:157], 0, v[174:175]
	global_load_dwordx4 v[208:211], v[174:175], off
	global_load_dwordx4 v[216:219], v[174:175], off offset:64
	global_load_dwordx4 v[220:223], v[174:175], off offset:512
	global_load_dwordx4 v[224:227], v[174:175], off offset:576
	v_add_u32_e32 v174, 48, v158
	v_ashrrev_i32_e32 v175, 31, v174
	v_lshlrev_b64 v[174:175], 13, v[174:175]
	v_lshl_add_u64 v[174:175], v[156:157], 0, v[174:175]
	global_load_dwordx4 v[228:231], v[174:175], off
	global_load_dwordx4 v[232:235], v[174:175], off offset:64
	global_load_dwordx4 v[236:239], v[174:175], off offset:512
	global_load_dwordx4 v[240:243], v[174:175], off offset:576
	v_ashrrev_i32_e32 v215, 31, v158
	v_lshlrev_b64 v[214:215], 13, v[158:159]
	v_lshl_add_u64 v[214:215], v[156:157], 0, v[214:215]
	s_waitcnt vmcnt(15)
	v_pk_fma_f32 v[142:143], v[142:143], v[134:135], v[178:179]
	v_pk_fma_f32 v[140:141], v[140:141], v[132:133], v[176:177]
	global_store_dwordx4 v[214:215], v[140:143], off
	s_waitcnt vmcnt(15)
	v_pk_fma_f32 v[138:139], v[138:139], v[130:131], v[182:183]
	v_pk_fma_f32 v[136:137], v[136:137], v[128:129], v[180:181]
	global_store_dwordx4 v[214:215], v[136:139], off offset:64
	s_waitcnt vmcnt(15)
	v_pk_fma_f32 v[126:127], v[126:127], v[122:123], v[186:187]
	v_pk_fma_f32 v[124:125], v[124:125], v[120:121], v[184:185]
	global_store_dwordx4 v[214:215], v[124:127], off offset:512
	s_waitcnt vmcnt(15)
	v_pk_fma_f32 v[118:119], v[118:119], v[78:79], v[190:191]
	v_pk_fma_f32 v[116:117], v[116:117], v[76:77], v[188:189]
	global_store_dwordx4 v[214:215], v[116:119], off offset:576
	s_nop 1
	v_add_u32_e32 v214, 16, v158
	v_ashrrev_i32_e32 v215, 31, v214
	v_lshlrev_b64 v[214:215], 13, v[214:215]
	v_lshl_add_u64 v[214:215], v[156:157], 0, v[214:215]
	s_waitcnt vmcnt(15)
	v_pk_fma_f32 v[114:115], v[114:115], v[134:135], v[194:195]
	v_pk_fma_f32 v[112:113], v[112:113], v[132:133], v[192:193]
	global_store_dwordx4 v[214:215], v[112:115], off
	s_waitcnt vmcnt(15)
	v_pk_fma_f32 v[110:111], v[110:111], v[130:131], v[198:199]
	v_pk_fma_f32 v[108:109], v[108:109], v[128:129], v[196:197]
	global_store_dwordx4 v[214:215], v[108:111], off offset:64
	s_waitcnt vmcnt(15)
	v_pk_fma_f32 v[106:107], v[106:107], v[122:123], v[202:203]
	v_pk_fma_f32 v[104:105], v[104:105], v[120:121], v[200:201]
	global_store_dwordx4 v[214:215], v[104:107], off offset:512
	s_waitcnt vmcnt(15)
	v_pk_fma_f32 v[102:103], v[102:103], v[78:79], v[206:207]
	v_pk_fma_f32 v[100:101], v[100:101], v[76:77], v[204:205]
	global_store_dwordx4 v[214:215], v[100:103], off offset:576
	s_nop 1
	v_add_u32_e32 v214, 32, v158
	v_ashrrev_i32_e32 v215, 31, v214
	v_lshlrev_b64 v[214:215], 13, v[214:215]
	v_lshl_add_u64 v[214:215], v[156:157], 0, v[214:215]
	s_waitcnt vmcnt(15)
	v_pk_fma_f32 v[98:99], v[98:99], v[134:135], v[210:211]
	v_pk_fma_f32 v[96:97], v[96:97], v[132:133], v[208:209]
	global_store_dwordx4 v[214:215], v[96:99], off
	s_waitcnt vmcnt(15)
	v_pk_fma_f32 v[94:95], v[94:95], v[130:131], v[218:219]
	v_pk_fma_f32 v[92:93], v[92:93], v[128:129], v[216:217]
	global_store_dwordx4 v[214:215], v[92:95], off offset:64
	s_waitcnt vmcnt(15)
	v_pk_fma_f32 v[90:91], v[90:91], v[122:123], v[222:223]
	v_pk_fma_f32 v[88:89], v[88:89], v[120:121], v[220:221]
	global_store_dwordx4 v[214:215], v[88:91], off offset:512
	s_waitcnt vmcnt(15)
	v_pk_fma_f32 v[86:87], v[86:87], v[78:79], v[226:227]
	v_pk_fma_f32 v[84:85], v[84:85], v[76:77], v[224:225]
	global_store_dwordx4 v[214:215], v[84:87], off offset:576
	s_nop 1
	v_add_u32_e32 v214, 48, v158
	v_ashrrev_i32_e32 v215, 31, v214
	v_lshlrev_b64 v[214:215], 13, v[214:215]
	v_lshl_add_u64 v[214:215], v[156:157], 0, v[214:215]
	s_waitcnt vmcnt(15)
	v_pk_fma_f32 v[82:83], v[82:83], v[134:135], v[230:231]
	v_pk_fma_f32 v[80:81], v[80:81], v[132:133], v[228:229]
	global_store_dwordx4 v[214:215], v[80:83], off
	s_waitcnt vmcnt(15)
	v_pk_fma_f32 v[74:75], v[74:75], v[130:131], v[234:235]
	v_pk_fma_f32 v[72:73], v[72:73], v[128:129], v[232:233]
	global_store_dwordx4 v[214:215], v[72:75], off offset:64
	s_waitcnt vmcnt(15)
	v_pk_fma_f32 v[70:71], v[70:71], v[122:123], v[238:239]
	v_pk_fma_f32 v[68:69], v[68:69], v[120:121], v[236:237]
	global_store_dwordx4 v[214:215], v[68:71], off offset:512
	s_waitcnt vmcnt(15)
	v_pk_fma_f32 v[66:67], v[66:67], v[78:79], v[242:243]
	v_pk_fma_f32 v[64:65], v[64:65], v[76:77], v[240:241]
	global_store_dwordx4 v[214:215], v[64:67], off offset:576
	v_add_u32_e32 v174, 128, v158
	v_ashrrev_i32_e32 v175, 31, v174
	v_lshlrev_b64 v[174:175], 13, v[174:175]
	v_lshl_add_u64 v[174:175], v[156:157], 0, v[174:175]
	global_load_dwordx4 v[176:179], v[174:175], off
	global_load_dwordx4 v[180:183], v[174:175], off offset:64
	global_load_dwordx4 v[184:187], v[174:175], off offset:512
	global_load_dwordx4 v[188:191], v[174:175], off offset:576
	v_add_u32_e32 v174, 144, v158
	v_ashrrev_i32_e32 v175, 31, v174
	v_lshlrev_b64 v[174:175], 13, v[174:175]
	v_lshl_add_u64 v[174:175], v[156:157], 0, v[174:175]
	global_load_dwordx4 v[192:195], v[174:175], off
	global_load_dwordx4 v[196:199], v[174:175], off offset:64
	global_load_dwordx4 v[200:203], v[174:175], off offset:512
	global_load_dwordx4 v[204:207], v[174:175], off offset:576
	v_add_u32_e32 v174, 160, v158
	v_ashrrev_i32_e32 v175, 31, v174
	v_lshlrev_b64 v[174:175], 13, v[174:175]
	v_lshl_add_u64 v[174:175], v[156:157], 0, v[174:175]
	global_load_dwordx4 v[208:211], v[174:175], off
	global_load_dwordx4 v[216:219], v[174:175], off offset:64
	global_load_dwordx4 v[220:223], v[174:175], off offset:512
	global_load_dwordx4 v[224:227], v[174:175], off offset:576
	v_add_u32_e32 v174, 176, v158
	v_ashrrev_i32_e32 v175, 31, v174
	v_lshlrev_b64 v[174:175], 13, v[174:175]
	v_lshl_add_u64 v[174:175], v[156:157], 0, v[174:175]
	global_load_dwordx4 v[228:231], v[174:175], off
	global_load_dwordx4 v[232:235], v[174:175], off offset:64
	global_load_dwordx4 v[236:239], v[174:175], off offset:512
	global_load_dwordx4 v[240:243], v[174:175], off offset:576
	s_nop 1
	v_add_u32_e32 v214, 128, v158
	v_ashrrev_i32_e32 v215, 31, v214
	v_lshlrev_b64 v[214:215], 13, v[214:215]
	v_lshl_add_u64 v[214:215], v[156:157], 0, v[214:215]
	s_waitcnt vmcnt(15)
	v_pk_fma_f32 v[62:63], v[62:63], v[134:135], v[178:179]
	v_pk_fma_f32 v[60:61], v[60:61], v[132:133], v[176:177]
	global_store_dwordx4 v[214:215], v[60:63], off
	s_waitcnt vmcnt(15)
	v_pk_fma_f32 v[58:59], v[58:59], v[130:131], v[182:183]
	v_pk_fma_f32 v[56:57], v[56:57], v[128:129], v[180:181]
	global_store_dwordx4 v[214:215], v[56:59], off offset:64
	s_waitcnt vmcnt(15)
	v_pk_fma_f32 v[54:55], v[54:55], v[122:123], v[186:187]
	v_pk_fma_f32 v[52:53], v[52:53], v[120:121], v[184:185]
	global_store_dwordx4 v[214:215], v[52:55], off offset:512
	s_waitcnt vmcnt(15)
	v_pk_fma_f32 v[50:51], v[50:51], v[78:79], v[190:191]
	v_pk_fma_f32 v[48:49], v[48:49], v[76:77], v[188:189]
	global_store_dwordx4 v[214:215], v[48:51], off offset:576
	s_nop 1
	v_add_u32_e32 v214, 144, v158
	v_ashrrev_i32_e32 v215, 31, v214
	v_lshlrev_b64 v[214:215], 13, v[214:215]
	v_lshl_add_u64 v[214:215], v[156:157], 0, v[214:215]
	s_waitcnt vmcnt(15)
	v_pk_fma_f32 v[46:47], v[46:47], v[134:135], v[194:195]
	v_pk_fma_f32 v[44:45], v[44:45], v[132:133], v[192:193]
	global_store_dwordx4 v[214:215], v[44:47], off
	s_waitcnt vmcnt(15)
	v_pk_fma_f32 v[42:43], v[42:43], v[130:131], v[198:199]
	v_pk_fma_f32 v[40:41], v[40:41], v[128:129], v[196:197]
	global_store_dwordx4 v[214:215], v[40:43], off offset:64
	s_waitcnt vmcnt(15)
	v_pk_fma_f32 v[38:39], v[38:39], v[122:123], v[202:203]
	v_pk_fma_f32 v[36:37], v[36:37], v[120:121], v[200:201]
	global_store_dwordx4 v[214:215], v[36:39], off offset:512
	s_waitcnt vmcnt(15)
	v_pk_fma_f32 v[34:35], v[34:35], v[78:79], v[206:207]
	v_pk_fma_f32 v[32:33], v[32:33], v[76:77], v[204:205]
	global_store_dwordx4 v[214:215], v[32:35], off offset:576
	s_nop 1
	v_add_u32_e32 v214, 160, v158
	v_ashrrev_i32_e32 v215, 31, v214
	v_lshlrev_b64 v[214:215], 13, v[214:215]
	v_lshl_add_u64 v[214:215], v[156:157], 0, v[214:215]
	s_waitcnt vmcnt(15)
	v_pk_fma_f32 v[30:31], v[30:31], v[134:135], v[210:211]
	v_pk_fma_f32 v[28:29], v[28:29], v[132:133], v[208:209]
	global_store_dwordx4 v[214:215], v[28:31], off
	s_waitcnt vmcnt(15)
	v_pk_fma_f32 v[26:27], v[26:27], v[130:131], v[218:219]
	v_pk_fma_f32 v[24:25], v[24:25], v[128:129], v[216:217]
	global_store_dwordx4 v[214:215], v[24:27], off offset:64
	s_waitcnt vmcnt(15)
	v_pk_fma_f32 v[22:23], v[22:23], v[122:123], v[222:223]
	v_pk_fma_f32 v[20:21], v[20:21], v[120:121], v[220:221]
	global_store_dwordx4 v[214:215], v[20:23], off offset:512
	s_waitcnt vmcnt(15)
	v_pk_fma_f32 v[14:15], v[14:15], v[78:79], v[226:227]
	v_pk_fma_f32 v[12:13], v[12:13], v[76:77], v[224:225]
	global_store_dwordx4 v[214:215], v[12:15], off offset:576
	s_nop 1
	v_add_u32_e32 v214, 176, v158
	v_ashrrev_i32_e32 v215, 31, v214
	v_lshlrev_b64 v[214:215], 13, v[214:215]
	v_lshl_add_u64 v[214:215], v[156:157], 0, v[214:215]
	s_waitcnt vmcnt(15)
	v_pk_fma_f32 v[18:19], v[18:19], v[134:135], v[230:231]
	v_pk_fma_f32 v[16:17], v[16:17], v[132:133], v[228:229]
	global_store_dwordx4 v[214:215], v[16:19], off
	s_waitcnt vmcnt(15)
	v_pk_fma_f32 v[10:11], v[10:11], v[130:131], v[234:235]
	v_pk_fma_f32 v[8:9], v[8:9], v[128:129], v[232:233]
	global_store_dwordx4 v[214:215], v[8:11], off offset:64
	s_waitcnt vmcnt(15)
	v_pk_fma_f32 v[6:7], v[6:7], v[122:123], v[238:239]
	v_pk_fma_f32 v[4:5], v[4:5], v[120:121], v[236:237]
	global_store_dwordx4 v[214:215], v[4:7], off offset:512
	s_waitcnt vmcnt(15)
	v_pk_fma_f32 v[2:3], v[2:3], v[78:79], v[242:243]
	v_pk_fma_f32 v[0:1], v[0:1], v[76:77], v[240:241]
	global_store_dwordx4 v[214:215], v[0:3], off offset:576
	s_cbranch_vccnz .LBB0_1327
	s_andn2_b64 vcc, exec, s[2:3]
	s_cbranch_vccnz .LBB0_1326
	s_barrier
	s_branch .LBB0_1326
